# phase 4: half of the workgroups (whole retention sibling groups) run the retention scans before their attention items, so MFMA-bound and memory-bound work overlap chip-wide
# speedup vs baseline: 1.0143x; 1.0108x over previous
.LBB0_3:
	s_or_b64 exec, exec, s[4:5]
	v_writelane_b32 v252, s16, 3
	s_cmp_le_i32 s19, s18
	s_waitcnt lgkmcnt(0)
	v_writelane_b32 v252, s17, 4
	v_writelane_b32 v252, s18, 5
	v_writelane_b32 v252, s19, 6
	s_barrier
	s_cbranch_scc1 .LBB0_454
	s_load_dwordx16 s[36:51], s[0:1], 0x40
	s_load_dwordx16 s[52:67], s[0:1], 0x80
	s_load_dwordx4 s[16:19], s[0:1], 0xc0
	v_lshrrev_b32_e32 v2, 20, v0
	v_lshrrev_b32_e32 v0, 10, v0
	v_or_b32_e32 v0, v0, v2
	v_mov_b32_e32 v230, 0x358637bd
	s_mov_b32 s4, 0
	v_writelane_b32 v255, s4, 62
	s_waitcnt lgkmcnt(0)
	s_sub_i32 s4, s19, s18
	s_cmp_gt_i32 s4, 1
	s_cselect_b64 s[4:5], -1, 0
	s_lshr_b32 s98, s9, 6
	s_lshl_b32 s99, s3, 3
	v_writelane_b32 v252, s4, 7
	s_cmpk_eq_i32 s3, 0x100
	v_mov_b32_e32 v233, 1.0
	v_writelane_b32 v252, s5, 8
	s_cselect_b64 s[4:5], -1, 0
	v_writelane_b32 v252, s4, 9
	v_mov_b32_e32 v232, 1
	v_bfrev_b32_e32 v234, 0.5
	v_writelane_b32 v252, s5, 10
	s_add_u32 s4, s66, 0x14000000
	s_addc_u32 s5, s67, 0
	v_writelane_b32 v252, s4, 11
	s_lshr_b32 s2, s3, 3
	v_mov_b32_e32 v235, 0x10800
	v_writelane_b32 v252, s5, 12
	s_add_u32 s4, s66, 0x14800000
	v_writelane_b32 v252, s52, 13
	s_addc_u32 s5, s67, 0
	s_cmp_lg_u64 s[48:49], 0
	v_writelane_b32 v252, s53, 14
	v_writelane_b32 v252, s54, 15
	v_writelane_b32 v252, s55, 16
	v_writelane_b32 v252, s56, 17
	v_writelane_b32 v252, s57, 18
	v_writelane_b32 v252, s58, 19
	v_writelane_b32 v252, s59, 20
	v_writelane_b32 v252, s60, 21
	v_writelane_b32 v252, s61, 22
	v_writelane_b32 v252, s62, 23
	v_writelane_b32 v252, s63, 24
	v_writelane_b32 v252, s64, 25
	v_writelane_b32 v252, s65, 26
	v_writelane_b32 v252, s66, 27
	v_writelane_b32 v252, s67, 28
	v_writelane_b32 v252, s4, 29
	s_load_dwordx16 s[64:79], s[0:1], 0x0
	v_mov_b32_e32 v231, 0x12900
	v_writelane_b32 v252, s5, 30
	s_cselect_b64 s[4:5], -1, 0
	v_writelane_b32 v252, s4, 31
	s_mov_b32 s61, 0x800000
	s_mov_b32 s34, 0x18000
	v_writelane_b32 v252, s5, 32
	v_writelane_b32 v252, s36, 33
	s_cmp_lg_u64 s[44:45], 0
	s_cselect_b64 s[4:5], -1, 0
	v_writelane_b32 v252, s37, 34
	v_writelane_b32 v252, s38, 35
	v_writelane_b32 v252, s39, 36
	v_writelane_b32 v252, s40, 37
	v_writelane_b32 v252, s41, 38
	v_writelane_b32 v252, s42, 39
	v_writelane_b32 v252, s43, 40
	v_writelane_b32 v252, s44, 41
	v_writelane_b32 v252, s45, 42
	v_writelane_b32 v252, s46, 43
	v_writelane_b32 v252, s47, 44
	v_writelane_b32 v252, s48, 45
	v_writelane_b32 v252, s49, 46
	v_writelane_b32 v252, s50, 47
	v_writelane_b32 v252, s51, 48
	v_writelane_b32 v252, s4, 49
	s_cmp_gt_i32 s19, 64
	s_movk_i32 s19, 0x580
	v_writelane_b32 v252, s5, 50
	s_cselect_b64 s[4:5], -1, 0
	v_writelane_b32 v252, s4, 51
	s_cmp_lt_u32 s9, 64
	s_mov_b32 s35, 0
	v_writelane_b32 v252, s5, 52
	s_movk_i32 s4, 0x3ff
	v_and_or_b32 v0, v0, s4, v1
	s_cselect_b64 s[4:5], -1, 0
	v_writelane_b32 v252, s4, 53
	v_mov_b32_e32 v1, 0
	s_mov_b64 s[54:55], 0x16db700
	v_writelane_b32 v252, s5, 54
	s_add_u32 s4, s16, 0x36200
	s_addc_u32 s5, s17, 0
	v_writelane_b32 v252, s4, 55
	s_mov_b64 s[92:93], 0x16eb700
	s_mov_b64 s[24:25], 0x16db780
	v_writelane_b32 v252, s5, 56
	s_add_u32 s4, s16, 0x36400
	s_addc_u32 s5, s17, 0
	v_writelane_b32 v252, s4, 57
	s_mov_b64 s[96:97], 0x166b680
	s_mov_b64 s[26:27], 0x165b700
	v_writelane_b32 v252, s5, 58
	s_add_u32 s4, s16, 0x36500
	s_addc_u32 s5, s17, 0
	v_writelane_b32 v252, s4, 59
	s_mov_b64 s[22:23], 0x166b700
	s_mov_b64 s[28:29], 0x165b780
	v_writelane_b32 v252, s5, 60
	s_add_u32 s4, s16, 0x36600
	s_addc_u32 s5, s17, 0
	v_writelane_b32 v252, s4, 61
	s_mov_b64 s[30:31], 0x1553680
	s_mov_b64 s[46:47], 0x153b700
	v_writelane_b32 v252, s5, 62
	s_add_u32 s4, s16, 0x36700
	s_addc_u32 s5, s17, 0
	v_writelane_b32 v252, s4, 63
	s_mov_b64 s[56:57], 0x1553700
	s_mov_b64 s[58:59], 0x153b780
	v_writelane_b32 v253, s5, 0
	s_add_u32 s4, s16, 0x36800
	s_addc_u32 s5, s17, 0
	v_writelane_b32 v253, s4, 1
	s_mov_b32 s60, 0x3dd53b94
	s_nop 0
	v_writelane_b32 v253, s5, 2
	s_add_u32 s4, s16, 0x36900
	s_addc_u32 s5, s17, 0
	v_writelane_b32 v253, s4, 3
	s_nop 1
	v_writelane_b32 v253, s5, 4
	s_add_u32 s4, s16, 0x36a00
	s_addc_u32 s5, s17, 0
	v_writelane_b32 v253, s4, 5
	s_nop 1
	v_writelane_b32 v253, s5, 6
	s_add_u32 s4, s16, 0x36b00
	s_addc_u32 s5, s17, 0
	v_writelane_b32 v253, s4, 7
	s_nop 1
	v_writelane_b32 v253, s5, 8
	s_add_u32 s4, s16, 0x36c00
	s_addc_u32 s5, s17, 0
	v_writelane_b32 v253, s4, 9
	s_nop 1
	v_writelane_b32 v253, s5, 10
	s_add_u32 s4, s16, 0x36d00
	s_addc_u32 s5, s17, 0
	v_writelane_b32 v253, s4, 11
	s_nop 1
	v_writelane_b32 v253, s5, 12
	s_add_u32 s4, s16, 0x36e00
	s_addc_u32 s5, s17, 0
	v_writelane_b32 v253, s4, 13
	s_nop 1
	v_writelane_b32 v253, s5, 14
	s_add_u32 s4, s16, 0x36f00
	s_addc_u32 s5, s17, 0
	v_writelane_b32 v253, s4, 15
	s_nop 1
	v_writelane_b32 v253, s5, 16
	s_add_u32 s4, s16, 0x37000
	s_addc_u32 s5, s17, 0
	v_writelane_b32 v253, s4, 17
	s_nop 1
	v_writelane_b32 v253, s5, 18
	s_add_u32 s4, s16, 0x37100
	s_addc_u32 s5, s17, 0
	v_writelane_b32 v253, s4, 19
	s_nop 1
	v_writelane_b32 v253, s5, 20
	s_add_u32 s4, s16, 0x37200
	s_addc_u32 s5, s17, 0
	v_writelane_b32 v253, s4, 21
	s_nop 1
	v_writelane_b32 v253, s5, 22
	s_add_u32 s4, s16, 0x37300
	s_addc_u32 s5, s17, 0
	v_writelane_b32 v253, s4, 23
	s_cmp_eq_u32 s8, 15
	s_nop 0
	v_writelane_b32 v253, s5, 24
	s_cselect_b64 s[4:5], -1, 0
	v_writelane_b32 v253, s4, 25
	s_cmp_eq_u32 s8, 14
	s_nop 0
	v_writelane_b32 v253, s5, 26
	s_cselect_b64 s[4:5], -1, 0
	v_writelane_b32 v253, s4, 27
	s_cmp_eq_u32 s8, 13
	s_nop 0
	v_writelane_b32 v253, s5, 28
	s_cselect_b64 s[4:5], -1, 0
	v_writelane_b32 v253, s4, 29
	s_cmp_eq_u32 s8, 12
	s_nop 0
	v_writelane_b32 v253, s5, 30
	s_cselect_b64 s[4:5], -1, 0
	v_writelane_b32 v253, s4, 31
	s_cmp_eq_u32 s8, 11
	s_nop 0
	v_writelane_b32 v253, s5, 32
	s_cselect_b64 s[4:5], -1, 0
	v_writelane_b32 v253, s4, 33
	s_cmp_eq_u32 s8, 10
	s_nop 0
	v_writelane_b32 v253, s5, 34
	s_cselect_b64 s[4:5], -1, 0
	v_writelane_b32 v253, s4, 35
	s_cmp_eq_u32 s8, 9
	s_nop 0
	v_writelane_b32 v253, s5, 36
	s_cselect_b64 s[4:5], -1, 0
	v_writelane_b32 v253, s4, 37
	s_cmp_eq_u32 s8, 8
	s_nop 0
	v_writelane_b32 v253, s5, 38
	s_cselect_b64 s[4:5], -1, 0
	v_writelane_b32 v253, s4, 39
	s_cmp_eq_u32 s8, 7
	s_nop 0
	v_writelane_b32 v253, s5, 40
	s_cselect_b64 s[4:5], -1, 0
	v_writelane_b32 v253, s4, 41
	s_cmp_eq_u32 s8, 6
	s_nop 0
	v_writelane_b32 v253, s5, 42
	s_cselect_b64 s[4:5], -1, 0
	v_writelane_b32 v253, s4, 43
	s_cmp_eq_u32 s8, 5
	s_nop 0
	v_writelane_b32 v253, s5, 44
	s_cselect_b64 s[4:5], -1, 0
	v_writelane_b32 v253, s4, 45
	s_cmp_eq_u32 s8, 4
	s_nop 0
	v_writelane_b32 v253, s5, 46
	s_cselect_b64 s[4:5], -1, 0
	v_writelane_b32 v253, s4, 47
	s_cmp_eq_u32 s8, 3
	s_nop 0
	v_writelane_b32 v253, s5, 48
	s_cselect_b64 s[4:5], -1, 0
	v_writelane_b32 v253, s4, 49
	s_cmp_eq_u32 s8, 2
	s_nop 0
	v_writelane_b32 v253, s5, 50
	s_cselect_b64 s[4:5], -1, 0
	v_writelane_b32 v253, s4, 51
	s_cmp_eq_u32 s8, 1
	s_nop 0
	v_writelane_b32 v253, s5, 52
	s_cselect_b64 s[4:5], -1, 0
	v_writelane_b32 v253, s4, 53
	s_cmp_eq_u32 s8, 0
	s_nop 0
	v_writelane_b32 v253, s5, 54
	s_cselect_b64 s[4:5], -1, 0
	v_writelane_b32 v253, s4, 55
	s_nop 1
	v_writelane_b32 v253, s5, 56
	s_lshl_b32 s4, s8, 8
	s_add_u32 s4, s12, s4
	s_mov_b32 s5, s3
	s_addc_u32 s3, s13, 0
	s_add_u32 s6, s4, 0x1400
	s_addc_u32 s7, s3, 0
	v_writelane_b32 v253, s6, 57
	s_movk_i32 s12, 0x180
	s_nop 0
	v_writelane_b32 v253, s7, 58
	s_add_u32 s6, s4, 0x2400
	s_addc_u32 s7, s3, 0
	v_writelane_b32 v253, s6, 59
	s_nop 1
	v_writelane_b32 v253, s7, 60
	s_add_u32 s6, s16, 0x39400
	s_addc_u32 s7, s17, 0
	v_writelane_b32 v253, s6, 61
	s_nop 1
	v_writelane_b32 v253, s7, 62
	s_add_u32 s6, s16, 0x39500
	s_addc_u32 s7, s17, 0
	s_lshl_b32 s33, s5, 11
	v_writelane_b32 v253, s6, 63
	s_add_u32 s3, s16, 0x27f9b608
	s_nop 0
	v_writelane_b32 v254, s7, 0
	v_writelane_b32 v254, s3, 1
	s_addc_u32 s3, s17, 0
	v_writelane_b32 v254, s3, 2
	s_bitcmp1_b32 s5, 0
	v_writelane_b32 v254, s5, 3
	s_cselect_b64 s[4:5], -1, 0
	v_writelane_b32 v254, s4, 4
	s_nop 1
	v_writelane_b32 v254, s5, 5
	v_writelane_b32 v254, s2, 6
	s_lshl_b32 s2, s2, 5
	v_writelane_b32 v254, s2, 7
	s_add_i32 s2, 0, 0x11000
	v_writelane_b32 v254, s2, 8
	s_add_i32 s2, 0, 0x22000
	v_writelane_b32 v254, s2, 9
	s_add_i32 s2, 0, 0x22200
	v_writelane_b32 v254, s2, 10
	s_add_i32 s2, 0, 0x22400
	v_writelane_b32 v254, s2, 11
	s_add_i32 s2, 0, 0x22600
	v_writelane_b32 v254, s2, 12
	s_add_i32 s2, 0, 0x1dc00
	v_writelane_b32 v254, s2, 13
	s_add_i32 s2, 0, 0x19800
	v_writelane_b32 v254, s2, 14
	s_add_i32 s2, 0, 0x23ff0
	v_writelane_b32 v254, s2, 15
	s_add_i32 s2, 0, 0x23ff4
	v_writelane_b32 v254, s2, 16
	v_cmp_eq_u32_e64 s[2:3], 0, v0
	s_nop 1
	v_writelane_b32 v254, s2, 17
	s_nop 1
	v_writelane_b32 v254, s3, 18
	s_waitcnt lgkmcnt(0)
	v_writelane_b32 v254, s64, 19
	s_mov_b64 s[2:3], 0x16eb680
	s_nop 0
	v_writelane_b32 v254, s65, 20
	v_writelane_b32 v254, s66, 21
	v_writelane_b32 v254, s67, 22
	v_writelane_b32 v254, s68, 23
	v_writelane_b32 v254, s69, 24
	v_writelane_b32 v254, s70, 25
	v_writelane_b32 v254, s71, 26
	v_writelane_b32 v254, s72, 27
	v_writelane_b32 v254, s73, 28
	v_writelane_b32 v254, s74, 29
	v_writelane_b32 v254, s75, 30
	v_writelane_b32 v254, s76, 31
	v_writelane_b32 v254, s77, 32
	v_writelane_b32 v254, s78, 33
	v_writelane_b32 v254, s79, 34
	v_writelane_b32 v254, s33, 35
	v_writelane_b32 v254, s98, 36
	s_branch .LBB0_8

.Lp4_attn_entry:
	s_mov_b32 s0, s35
	s_mov_b32 s1, s98
	s_mov_b32 s4, -1
	v_mbcnt_lo_u32_b32 v0, -1, 0
	v_readlane_b32 s6, v252, 0
	v_mbcnt_hi_u32_b32 v0, s4, v0
	v_lshl_add_u32 v2, s1, 6, v0
	s_cmpk_gt_i32 s6, 0x4ff
	v_readfirstlane_b32 s4, v2
	s_cbranch_scc1 .LBB0_43
	v_readlane_b32 s5, v255, 62
	s_nop 3
	s_cmp_eq_u32 s5, 2
	s_cbranch_scc1 .Lp4_go_attn
	s_bfe_u32 s5, s6, 0x10006
	s_nop 0
	v_writelane_b32 v255, s5, 62
	s_cmp_eq_u32 s5, 1
	s_cbranch_scc1 .LBB0_43
.Lp4_go_attn:
	v_readlane_b32 s40, v252, 3
	v_readlane_b32 s41, v252, 4
	s_add_u32 s5, s40, s0
	s_addc_u32 s10, s41, 0
	s_add_u32 s7, s5, 0x1899b600
	s_addc_u32 s8, s10, 0
	s_add_u32 s9, s5, 0x2019b600
	s_addc_u32 s48, s10, 0
	s_add_u32 s49, s5, 0x27f9b600
	s_addc_u32 s50, s10, 0
	s_ashr_i32 s4, s4, 6
	s_add_u32 s51, s5, 0x1a19b600
	s_addc_u32 s52, s10, 0
	s_add_u32 s53, s5, 0x2199b600
	s_addc_u32 s62, s10, 0
	s_add_u32 s63, s5, 0x28f9b600
	s_addc_u32 s64, s10, 0
	s_add_u32 s36, s5, 0x205b600
	s_mov_b32 s5, 0x2aaaaaab
	v_add_u32_e32 v9, 0x200, v2
	v_mul_hi_i32 v10, v9, s5
	v_lshrrev_b32_e32 v11, 31, v10
	v_ashrrev_i32_e32 v10, 2, v10
	s_addc_u32 s37, s10, 0
	s_movk_i32 s10, 0x190
	v_add_u32_e32 v10, v10, v11
	v_mul_lo_u32 v11, v10, s10
	v_mul_lo_u32 v10, v10, 24
	v_sub_u32_e32 v9, v9, v10
	v_add_u32_e32 v10, 0x400, v2
	v_mul_hi_i32 v12, v10, s5
	v_lshrrev_b32_e32 v13, 31, v12
	v_ashrrev_i32_e32 v12, 2, v12
	v_add_u32_e32 v12, v12, v13
	v_ashrrev_i32_e32 v188, 3, v2
	v_mul_hi_i32 v7, v2, s5
	v_mul_lo_u32 v13, v12, s10
	v_mul_lo_u32 v12, v12, 24
	s_movk_i32 s5, 0x90
	v_bfe_u32 v0, v2, 5, 1
	v_and_b32_e32 v5, 31, v2
	v_and_b32_e32 v6, 7, v2
	v_sub_u32_e32 v10, v10, v12
	v_mul_lo_u32 v12, v188, s5
	v_readlane_b32 s11, v254, 8
	v_lshlrev_b32_e32 v4, 3, v6
	v_lshlrev_b32_e32 v192, 3, v0
	v_add_u32_e32 v14, 0, v12
	v_lshlrev_b32_e32 v194, 4, v6
	v_add_u32_e32 v6, s11, v12
	v_mad_u32_u24 v12, v5, s10, 0
	v_lshlrev_b32_e32 v15, 4, v0
	v_lshlrev_b32_e32 v0, 8, v5
	v_lshl_or_b32 v193, s4, 5, v5
	v_lshrrev_b32_e32 v8, 31, v7
	v_ashrrev_i32_e32 v7, 2, v7
	s_cmp_gt_i32 s4, 3
	v_sub_u32_e32 v16, v12, v0
	v_lshlrev_b32_e32 v0, 2, v2
	s_movk_i32 s4, 0x80
	v_add_u32_e32 v7, v7, v8
	v_bitop3_b32 v214, v0, s4, v234 bitop3:0x6c
	v_mov_b32_e32 v0, s11
	s_movk_i32 s4, 0x110
	v_ashrrev_i32_e32 v3, 31, v2
	v_mul_lo_u32 v8, v7, s10
	v_mul_lo_u32 v7, v7, 24
	v_mad_u32_u24 v5, v5, s5, v0
	v_mul_lo_u32 v0, v193, s4
	v_lshlrev_b64 v[190:191], 3, v[2:3]
	v_ashrrev_i32_e32 v189, 31, v188
	v_sub_u32_e32 v7, v2, v7
	v_add_u32_e32 v17, 0, v0
	v_ashrrev_i32_e32 v196, 4, v2
	v_lshlrev_b32_e32 v0, 4, v2
	v_lshlrev_b64 v[198:199], 4, v[2:3]
	v_mov_b64_e32 v[2:3], 0x80
	v_add_u32_e32 v8, 0, v8
	v_lshlrev_b32_e32 v7, 4, v7
	v_add_u32_e32 v11, 0, v11
	v_lshlrev_b32_e32 v9, 4, v9
	v_add_u32_e32 v13, 0, v13
	v_lshlrev_b32_e32 v10, 4, v10
	v_and_b32_e32 v0, 0xf0, v0
	v_lshl_add_u64 v[200:201], v[188:189], 1, v[2:3]
	v_mul_lo_u32 v2, v196, s4
	s_mov_b32 s1, s35
	s_cselect_b64 s[38:39], -1, 0
	v_mov_b32_e32 v195, v1
	v_lshl_add_u64 v[202:203], s[40:41], 0, v[0:1]
	v_ashrrev_i32_e32 v197, 31, v196
	v_add3_u32 v189, v2, v0, 0
	v_lshlrev_b32_e32 v0, 1, v4
	v_add_u32_e32 v201, v6, v194
	v_add_u32_e32 v215, v12, v15
	v_add_u32_e32 v216, v16, v15
	v_add_u32_e32 v217, v5, v15
	v_add_u32_e32 v218, v17, v192
	v_add_u32_e32 v219, v8, v7
	v_add_u32_e32 v220, v11, v9
	v_add_u32_e32 v221, v13, v10
	v_add_u32_e32 v222, v14, v194
	v_readlane_b32 s42, v252, 5
	v_readlane_b32 s43, v252, 6

.LBB0_41:
	v_lshl_add_u64 v[10:11], v[8:9], 0, s[0:1]
	v_add_co_u32_e32 v12, vcc, 0x219b000, v10
	v_add_u32_e32 v14, s4, v189
	s_nop 0
	v_addc_co_u32_e32 v13, vcc, 0, v11, vcc
	global_load_dwordx4 v[16:19], v[12:13], off offset:1536
	ds_read_b128 v[2:5], v14
	s_mov_b32 s5, 0x3739b000
	s_add_i32 s4, s4, 0x8800
	v_lshl_add_u64 v[8:9], v[8:9], 0, s[16:17]
	s_cmp_eq_u32 s4, 0x11000
	s_waitcnt lgkmcnt(0)
	v_lshlrev_b32_e32 v12, 16, v2
	v_and_b32_e32 v13, 0xffff0000, v2
	s_waitcnt vmcnt(0)
	v_lshlrev_b32_e32 v15, 16, v16
	v_and_b32_e32 v2, 0xffff0000, v16
	v_mul_f32_e32 v16, 0xbfb8aa3b, v15
	v_exp_f32_e32 v20, v16
	v_mul_f32_e32 v16, 0xbfb8aa3b, v2
	v_exp_f32_e32 v21, v16
	s_nop 0
	v_pk_add_f32 v[20:21], v[20:21], 1.0 op_sel_hi:[1,0]
	s_nop 0
	v_div_scale_f32 v16, s[10:11], v21, v21, v2
	v_rcp_f32_e32 v22, v16
	s_nop 0
	v_fma_f32 v23, -v16, v22, 1.0
	v_fmac_f32_e32 v22, v23, v22
	v_div_scale_f32 v23, vcc, v2, v21, v2
	v_mul_f32_e32 v24, v23, v22
	v_fma_f32 v25, -v16, v24, v23
	v_fmac_f32_e32 v24, v25, v22
	v_fma_f32 v16, -v16, v24, v23
	v_div_fmas_f32 v16, v16, v22, v24
	v_div_fixup_f32 v21, v16, v21, v2
	v_div_scale_f32 v2, s[10:11], v20, v20, v15
	v_rcp_f32_e32 v16, v2
	s_nop 0
	v_fma_f32 v22, -v2, v16, 1.0
	v_fmac_f32_e32 v16, v22, v16
	v_div_scale_f32 v22, vcc, v15, v20, v15
	v_mul_f32_e32 v23, v22, v16
	v_fma_f32 v24, -v2, v23, v22
	v_fmac_f32_e32 v23, v24, v16
	v_fma_f32 v2, -v2, v23, v22
	v_div_fmas_f32 v2, v2, v16, v23
	v_div_fixup_f32 v20, v2, v20, v15
	v_pk_mul_f32 v[12:13], v[20:21], v[12:13]
	v_lshlrev_b32_e32 v15, 16, v17
	v_cvt_pk_bf16_f32 v2, v12, v13
	v_lshlrev_b32_e32 v12, 16, v3
	v_and_b32_e32 v13, 0xffff0000, v3
	v_and_b32_e32 v3, 0xffff0000, v17
	v_mul_f32_e32 v16, 0xbfb8aa3b, v15
	v_mul_f32_e32 v17, 0xbfb8aa3b, v3
	v_exp_f32_e32 v16, v16
	v_exp_f32_e32 v17, v17
	s_nop 0
	v_pk_add_f32 v[16:17], v[16:17], 1.0 op_sel_hi:[1,0]
	s_nop 0
	v_div_scale_f32 v20, s[10:11], v17, v17, v3
	v_rcp_f32_e32 v21, v20
	s_nop 0
	v_fma_f32 v22, -v20, v21, 1.0
	v_fmac_f32_e32 v21, v22, v21
	v_div_scale_f32 v22, vcc, v3, v17, v3
	v_mul_f32_e32 v23, v22, v21
	v_fma_f32 v24, -v20, v23, v22
	v_fmac_f32_e32 v23, v24, v21
	v_fma_f32 v20, -v20, v23, v22
	v_div_fmas_f32 v20, v20, v21, v23
	v_div_fixup_f32 v17, v20, v17, v3
	v_div_scale_f32 v3, s[10:11], v16, v16, v15
	v_rcp_f32_e32 v20, v3
	s_nop 0
	v_fma_f32 v21, -v3, v20, 1.0
	v_fmac_f32_e32 v20, v21, v20
	v_div_scale_f32 v21, vcc, v15, v16, v15
	v_mul_f32_e32 v22, v21, v20
	v_fma_f32 v23, -v3, v22, v21
	v_fmac_f32_e32 v22, v23, v20
	v_fma_f32 v3, -v3, v22, v21
	v_div_fmas_f32 v3, v3, v20, v22
	v_div_fixup_f32 v16, v3, v16, v15
	v_pk_mul_f32 v[12:13], v[16:17], v[12:13]
	v_lshlrev_b32_e32 v15, 16, v18
	v_cvt_pk_bf16_f32 v3, v12, v13
	v_lshlrev_b32_e32 v12, 16, v4
	v_and_b32_e32 v13, 0xffff0000, v4
	v_and_b32_e32 v4, 0xffff0000, v18
	v_mul_f32_e32 v16, 0xbfb8aa3b, v15
	v_mul_f32_e32 v17, 0xbfb8aa3b, v4
	v_exp_f32_e32 v16, v16
	v_exp_f32_e32 v17, v17
	s_nop 0
	v_pk_add_f32 v[16:17], v[16:17], 1.0 op_sel_hi:[1,0]
	s_nop 0
	v_div_scale_f32 v18, s[10:11], v17, v17, v4
	v_rcp_f32_e32 v20, v18
	s_nop 0
	v_fma_f32 v21, -v18, v20, 1.0
	v_fmac_f32_e32 v20, v21, v20
	v_div_scale_f32 v21, vcc, v4, v17, v4
	v_mul_f32_e32 v22, v21, v20
	v_fma_f32 v23, -v18, v22, v21
	v_fmac_f32_e32 v22, v23, v20
	v_fma_f32 v18, -v18, v22, v21
	v_div_fmas_f32 v18, v18, v20, v22
	v_div_fixup_f32 v17, v18, v17, v4
	v_div_scale_f32 v4, s[10:11], v16, v16, v15
	v_rcp_f32_e32 v18, v4
	s_nop 0
	v_fma_f32 v20, -v4, v18, 1.0
	v_fmac_f32_e32 v18, v20, v18
	v_div_scale_f32 v20, vcc, v15, v16, v15
	v_mul_f32_e32 v21, v20, v18
	v_fma_f32 v22, -v4, v21, v20
	v_fmac_f32_e32 v21, v22, v18
	v_fma_f32 v4, -v4, v21, v20
	v_div_fmas_f32 v4, v4, v18, v21
	v_div_fixup_f32 v16, v4, v16, v15
	v_pk_mul_f32 v[12:13], v[16:17], v[12:13]
	v_lshlrev_b32_e32 v15, 16, v19
	v_cvt_pk_bf16_f32 v4, v12, v13
	v_lshlrev_b32_e32 v12, 16, v5
	v_and_b32_e32 v13, 0xffff0000, v5
	v_and_b32_e32 v5, 0xffff0000, v19
	v_mul_f32_e32 v16, 0xbfb8aa3b, v15
	v_mul_f32_e32 v17, 0xbfb8aa3b, v5
	v_exp_f32_e32 v16, v16
	v_exp_f32_e32 v17, v17
	s_nop 0
	v_pk_add_f32 v[16:17], v[16:17], 1.0 op_sel_hi:[1,0]
	s_nop 0
	v_div_scale_f32 v18, s[10:11], v17, v17, v5
	v_rcp_f32_e32 v19, v18
	s_nop 0
	v_fma_f32 v20, -v18, v19, 1.0
	v_fmac_f32_e32 v19, v20, v19
	v_div_scale_f32 v20, vcc, v5, v17, v5
	v_mul_f32_e32 v21, v20, v19
	v_fma_f32 v22, -v18, v21, v20
	v_fmac_f32_e32 v21, v22, v19
	v_fma_f32 v18, -v18, v21, v20
	v_div_fmas_f32 v18, v18, v19, v21
	v_div_fixup_f32 v17, v18, v17, v5
	v_div_scale_f32 v5, s[10:11], v16, v16, v15
	v_rcp_f32_e32 v18, v5
	s_nop 0
	v_fma_f32 v19, -v5, v18, 1.0
	v_fmac_f32_e32 v18, v19, v18
	v_div_scale_f32 v19, vcc, v15, v16, v15
	v_mul_f32_e32 v20, v19, v18
	v_fma_f32 v21, -v5, v20, v19
	v_fmac_f32_e32 v20, v21, v18
	v_fma_f32 v5, -v5, v20, v19
	v_div_fmas_f32 v5, v5, v18, v20
	v_div_fixup_f32 v16, v5, v16, v15
	v_pk_mul_f32 v[12:13], v[16:17], v[12:13]
	s_nop 0
	v_cvt_pk_bf16_f32 v5, v12, v13
	v_lshl_add_u64 v[12:13], v[6:7], 0, s[0:1]
	v_add_co_u32_e32 v16, vcc, s5, v12
	s_mov_b32 s5, 0x21bb000
	s_nop 0
	v_addc_co_u32_e32 v17, vcc, 0, v13, vcc
	global_store_dwordx4 v[16:17], v[2:5], off offset:1536
	v_add_co_u32_e32 v16, vcc, s5, v10
	ds_read_b128 v[2:5], v14 offset:8704
	s_nop 0
	v_addc_co_u32_e32 v17, vcc, 0, v11, vcc
	global_load_dwordx4 v[16:19], v[16:17], off offset:1536
	s_mov_b32 s5, 0x373ab000
	s_waitcnt lgkmcnt(0)
	v_lshlrev_b32_e32 v20, 16, v2
	v_and_b32_e32 v21, 0xffff0000, v2
	v_lshl_add_u64 v[6:7], v[6:7], 0, s[14:15]
	s_waitcnt vmcnt(0)
	v_lshlrev_b32_e32 v15, 16, v16
	v_and_b32_e32 v2, 0xffff0000, v16
	v_mul_f32_e32 v16, 0xbfb8aa3b, v15
	v_exp_f32_e32 v22, v16
	v_mul_f32_e32 v16, 0xbfb8aa3b, v2
	v_exp_f32_e32 v23, v16
	s_nop 0
	v_pk_add_f32 v[22:23], v[22:23], 1.0 op_sel_hi:[1,0]
	s_nop 0
	v_div_scale_f32 v16, s[10:11], v23, v23, v2
	v_rcp_f32_e32 v24, v16
	s_nop 0
	v_fma_f32 v25, -v16, v24, 1.0
	v_fmac_f32_e32 v24, v25, v24
	v_div_scale_f32 v25, vcc, v2, v23, v2
	v_mul_f32_e32 v26, v25, v24
	v_fma_f32 v27, -v16, v26, v25
	v_fmac_f32_e32 v26, v27, v24
	v_fma_f32 v16, -v16, v26, v25
	v_div_fmas_f32 v16, v16, v24, v26
	v_div_fixup_f32 v23, v16, v23, v2
	v_div_scale_f32 v2, s[10:11], v22, v22, v15
	v_rcp_f32_e32 v16, v2
	s_nop 0
	v_fma_f32 v24, -v2, v16, 1.0
	v_fmac_f32_e32 v16, v24, v16
	v_div_scale_f32 v24, vcc, v15, v22, v15
	v_mul_f32_e32 v25, v24, v16
	v_fma_f32 v26, -v2, v25, v24
	v_fmac_f32_e32 v25, v26, v16
	v_fma_f32 v2, -v2, v25, v24
	v_div_fmas_f32 v2, v2, v16, v25
	v_div_fixup_f32 v22, v2, v22, v15
	v_pk_mul_f32 v[20:21], v[22:23], v[20:21]
	v_lshlrev_b32_e32 v15, 16, v17
	v_cvt_pk_bf16_f32 v2, v20, v21
	v_lshlrev_b32_e32 v20, 16, v3
	v_and_b32_e32 v21, 0xffff0000, v3
	v_and_b32_e32 v3, 0xffff0000, v17
	v_mul_f32_e32 v16, 0xbfb8aa3b, v15
	v_mul_f32_e32 v17, 0xbfb8aa3b, v3
	v_exp_f32_e32 v16, v16
	v_exp_f32_e32 v17, v17
	s_nop 0
	v_pk_add_f32 v[16:17], v[16:17], 1.0 op_sel_hi:[1,0]
	s_nop 0
	v_div_scale_f32 v22, s[10:11], v17, v17, v3
	v_rcp_f32_e32 v23, v22
	s_nop 0
	v_fma_f32 v24, -v22, v23, 1.0
	v_fmac_f32_e32 v23, v24, v23
	v_div_scale_f32 v24, vcc, v3, v17, v3
	v_mul_f32_e32 v25, v24, v23
	v_fma_f32 v26, -v22, v25, v24
	v_fmac_f32_e32 v25, v26, v23
	v_fma_f32 v22, -v22, v25, v24
	v_div_fmas_f32 v22, v22, v23, v25
	v_div_fixup_f32 v17, v22, v17, v3
	v_div_scale_f32 v3, s[10:11], v16, v16, v15
	v_rcp_f32_e32 v22, v3
	s_nop 0
	v_fma_f32 v23, -v3, v22, 1.0
	v_fmac_f32_e32 v22, v23, v22
	v_div_scale_f32 v23, vcc, v15, v16, v15
	v_mul_f32_e32 v24, v23, v22
	v_fma_f32 v25, -v3, v24, v23
	v_fmac_f32_e32 v24, v25, v22
	v_fma_f32 v3, -v3, v24, v23
	v_div_fmas_f32 v3, v3, v22, v24
	v_div_fixup_f32 v16, v3, v16, v15
	v_pk_mul_f32 v[16:17], v[16:17], v[20:21]
	v_lshlrev_b32_e32 v15, 16, v18
	v_cvt_pk_bf16_f32 v3, v16, v17
	v_lshlrev_b32_e32 v16, 16, v4
	v_and_b32_e32 v17, 0xffff0000, v4
	v_and_b32_e32 v4, 0xffff0000, v18
	v_mul_f32_e32 v18, 0xbfb8aa3b, v15
	v_exp_f32_e32 v20, v18
	v_mul_f32_e32 v18, 0xbfb8aa3b, v4
	v_exp_f32_e32 v21, v18
	s_nop 0
	v_pk_add_f32 v[20:21], v[20:21], 1.0 op_sel_hi:[1,0]
	s_nop 0
	v_div_scale_f32 v18, s[10:11], v21, v21, v4
	v_rcp_f32_e32 v22, v18
	s_nop 0
	v_fma_f32 v23, -v18, v22, 1.0
	v_fmac_f32_e32 v22, v23, v22
	v_div_scale_f32 v23, vcc, v4, v21, v4
	v_mul_f32_e32 v24, v23, v22
	v_fma_f32 v25, -v18, v24, v23
	v_fmac_f32_e32 v24, v25, v22
	v_fma_f32 v18, -v18, v24, v23
	v_div_fmas_f32 v18, v18, v22, v24
	v_div_fixup_f32 v21, v18, v21, v4
	v_div_scale_f32 v4, s[10:11], v20, v20, v15
	v_rcp_f32_e32 v18, v4
	s_nop 0
	v_fma_f32 v22, -v4, v18, 1.0
	v_fmac_f32_e32 v18, v22, v18
	v_div_scale_f32 v22, vcc, v15, v20, v15
	v_mul_f32_e32 v23, v22, v18
	v_fma_f32 v24, -v4, v23, v22
	v_fmac_f32_e32 v23, v24, v18
	v_fma_f32 v4, -v4, v23, v22
	v_div_fmas_f32 v4, v4, v18, v23
	v_div_fixup_f32 v20, v4, v20, v15
	v_pk_mul_f32 v[16:17], v[20:21], v[16:17]
	v_lshlrev_b32_e32 v15, 16, v19
	v_cvt_pk_bf16_f32 v4, v16, v17
	v_lshlrev_b32_e32 v16, 16, v5
	v_and_b32_e32 v17, 0xffff0000, v5
	v_and_b32_e32 v5, 0xffff0000, v19
	v_mul_f32_e32 v18, 0xbfb8aa3b, v15
	v_mul_f32_e32 v19, 0xbfb8aa3b, v5
	v_exp_f32_e32 v18, v18
	v_exp_f32_e32 v19, v19
	s_nop 0
	v_pk_add_f32 v[18:19], v[18:19], 1.0 op_sel_hi:[1,0]
	s_nop 0
	v_div_scale_f32 v20, s[10:11], v19, v19, v5
	v_rcp_f32_e32 v21, v20
	s_nop 0
	v_fma_f32 v22, -v20, v21, 1.0
	v_fmac_f32_e32 v21, v22, v21
	v_div_scale_f32 v22, vcc, v5, v19, v5
	v_mul_f32_e32 v23, v22, v21
	v_fma_f32 v24, -v20, v23, v22
	v_fmac_f32_e32 v23, v24, v21
	v_fma_f32 v20, -v20, v23, v22
	v_div_fmas_f32 v20, v20, v21, v23
	v_div_fixup_f32 v19, v20, v19, v5
	v_div_scale_f32 v5, s[10:11], v18, v18, v15
	v_rcp_f32_e32 v20, v5
	s_nop 0
	v_fma_f32 v21, -v5, v20, 1.0
	v_fmac_f32_e32 v20, v21, v20
	v_div_scale_f32 v21, vcc, v15, v18, v15
	v_mul_f32_e32 v22, v21, v20
	v_fma_f32 v23, -v5, v22, v21
	v_fmac_f32_e32 v22, v23, v20
	v_fma_f32 v5, -v5, v22, v21
	v_div_fmas_f32 v5, v5, v20, v22
	v_div_fixup_f32 v18, v5, v18, v15
	v_pk_mul_f32 v[16:17], v[18:19], v[16:17]
	s_nop 0
	v_cvt_pk_bf16_f32 v5, v16, v17
	v_add_co_u32_e32 v16, vcc, s5, v12
	s_mov_b32 s5, 0x21db000
	s_nop 0
	v_addc_co_u32_e32 v17, vcc, 0, v13, vcc
	global_store_dwordx4 v[16:17], v[2:5], off offset:1536
	v_add_co_u32_e32 v16, vcc, s5, v10
	ds_read_b128 v[2:5], v14 offset:17408
	s_nop 0
	v_addc_co_u32_e32 v17, vcc, 0, v11, vcc
	global_load_dwordx4 v[16:19], v[16:17], off offset:1536
	s_mov_b32 s5, 0x373bb000
	s_waitcnt lgkmcnt(0)
	v_lshlrev_b32_e32 v20, 16, v2
	v_and_b32_e32 v21, 0xffff0000, v2
	s_waitcnt vmcnt(0)
	v_lshlrev_b32_e32 v15, 16, v16
	v_and_b32_e32 v2, 0xffff0000, v16
	v_mul_f32_e32 v16, 0xbfb8aa3b, v15
	v_exp_f32_e32 v22, v16
	v_mul_f32_e32 v16, 0xbfb8aa3b, v2
	v_exp_f32_e32 v23, v16
	s_nop 0
	v_pk_add_f32 v[22:23], v[22:23], 1.0 op_sel_hi:[1,0]
	s_nop 0
	v_div_scale_f32 v16, s[10:11], v23, v23, v2
	v_rcp_f32_e32 v24, v16
	s_nop 0
	v_fma_f32 v25, -v16, v24, 1.0
	v_fmac_f32_e32 v24, v25, v24
	v_div_scale_f32 v25, vcc, v2, v23, v2
	v_mul_f32_e32 v26, v25, v24
	v_fma_f32 v27, -v16, v26, v25
	v_fmac_f32_e32 v26, v27, v24
	v_fma_f32 v16, -v16, v26, v25
	v_div_fmas_f32 v16, v16, v24, v26
	v_div_fixup_f32 v23, v16, v23, v2
	v_div_scale_f32 v2, s[10:11], v22, v22, v15
	v_rcp_f32_e32 v16, v2
	s_nop 0
	v_fma_f32 v24, -v2, v16, 1.0
	v_fmac_f32_e32 v16, v24, v16
	v_div_scale_f32 v24, vcc, v15, v22, v15
	v_mul_f32_e32 v25, v24, v16
	v_fma_f32 v26, -v2, v25, v24
	v_fmac_f32_e32 v25, v26, v16
	v_fma_f32 v2, -v2, v25, v24
	v_div_fmas_f32 v2, v2, v16, v25
	v_div_fixup_f32 v22, v2, v22, v15
	v_pk_mul_f32 v[20:21], v[22:23], v[20:21]
	v_lshlrev_b32_e32 v15, 16, v17
	v_cvt_pk_bf16_f32 v2, v20, v21
	v_lshlrev_b32_e32 v20, 16, v3
	v_and_b32_e32 v21, 0xffff0000, v3
	v_and_b32_e32 v3, 0xffff0000, v17
	v_mul_f32_e32 v16, 0xbfb8aa3b, v15
	v_mul_f32_e32 v17, 0xbfb8aa3b, v3
	v_exp_f32_e32 v16, v16
	v_exp_f32_e32 v17, v17
	s_nop 0
	v_pk_add_f32 v[16:17], v[16:17], 1.0 op_sel_hi:[1,0]
	s_nop 0
	v_div_scale_f32 v22, s[10:11], v17, v17, v3
	v_rcp_f32_e32 v23, v22
	s_nop 0
	v_fma_f32 v24, -v22, v23, 1.0
	v_fmac_f32_e32 v23, v24, v23
	v_div_scale_f32 v24, vcc, v3, v17, v3
	v_mul_f32_e32 v25, v24, v23
	v_fma_f32 v26, -v22, v25, v24
	v_fmac_f32_e32 v25, v26, v23
	v_fma_f32 v22, -v22, v25, v24
	v_div_fmas_f32 v22, v22, v23, v25
	v_div_fixup_f32 v17, v22, v17, v3
	v_div_scale_f32 v3, s[10:11], v16, v16, v15
	v_rcp_f32_e32 v22, v3
	s_nop 0
	v_fma_f32 v23, -v3, v22, 1.0
	v_fmac_f32_e32 v22, v23, v22
	v_div_scale_f32 v23, vcc, v15, v16, v15
	v_mul_f32_e32 v24, v23, v22
	v_fma_f32 v25, -v3, v24, v23
	v_fmac_f32_e32 v24, v25, v22
	v_fma_f32 v3, -v3, v24, v23
	v_div_fmas_f32 v3, v3, v22, v24
	v_div_fixup_f32 v16, v3, v16, v15
	v_pk_mul_f32 v[16:17], v[16:17], v[20:21]
	v_lshlrev_b32_e32 v15, 16, v18
	v_cvt_pk_bf16_f32 v3, v16, v17
	v_lshlrev_b32_e32 v16, 16, v4
	v_and_b32_e32 v17, 0xffff0000, v4
	v_and_b32_e32 v4, 0xffff0000, v18
	v_mul_f32_e32 v18, 0xbfb8aa3b, v15
	v_exp_f32_e32 v20, v18
	v_mul_f32_e32 v18, 0xbfb8aa3b, v4
	v_exp_f32_e32 v21, v18
	s_nop 0
	v_pk_add_f32 v[20:21], v[20:21], 1.0 op_sel_hi:[1,0]
	s_nop 0
	v_div_scale_f32 v18, s[10:11], v21, v21, v4
	v_rcp_f32_e32 v22, v18
	s_nop 0
	v_fma_f32 v23, -v18, v22, 1.0
	v_fmac_f32_e32 v22, v23, v22
	v_div_scale_f32 v23, vcc, v4, v21, v4
	v_mul_f32_e32 v24, v23, v22
	v_fma_f32 v25, -v18, v24, v23
	v_fmac_f32_e32 v24, v25, v22
	v_fma_f32 v18, -v18, v24, v23
	v_div_fmas_f32 v18, v18, v22, v24
	v_div_fixup_f32 v21, v18, v21, v4
	v_div_scale_f32 v4, s[10:11], v20, v20, v15
	v_rcp_f32_e32 v18, v4
	s_nop 0
	v_fma_f32 v22, -v4, v18, 1.0
	v_fmac_f32_e32 v18, v22, v18
	v_div_scale_f32 v22, vcc, v15, v20, v15
	v_mul_f32_e32 v23, v22, v18
	v_fma_f32 v24, -v4, v23, v22
	v_fmac_f32_e32 v23, v24, v18
	v_fma_f32 v4, -v4, v23, v22
	v_div_fmas_f32 v4, v4, v18, v23
	v_div_fixup_f32 v20, v4, v20, v15
	v_pk_mul_f32 v[16:17], v[20:21], v[16:17]
	v_lshlrev_b32_e32 v15, 16, v19
	v_cvt_pk_bf16_f32 v4, v16, v17
	v_lshlrev_b32_e32 v16, 16, v5
	v_and_b32_e32 v17, 0xffff0000, v5
	v_and_b32_e32 v5, 0xffff0000, v19
	v_mul_f32_e32 v18, 0xbfb8aa3b, v15
	v_mul_f32_e32 v19, 0xbfb8aa3b, v5
	v_exp_f32_e32 v18, v18
	v_exp_f32_e32 v19, v19
	s_nop 0
	v_pk_add_f32 v[18:19], v[18:19], 1.0 op_sel_hi:[1,0]
	s_nop 0
	v_div_scale_f32 v20, s[10:11], v19, v19, v5
	v_rcp_f32_e32 v21, v20
	s_nop 0
	v_fma_f32 v22, -v20, v21, 1.0
	v_fmac_f32_e32 v21, v22, v21
	v_div_scale_f32 v22, vcc, v5, v19, v5
	v_mul_f32_e32 v23, v22, v21
	v_fma_f32 v24, -v20, v23, v22
	v_fmac_f32_e32 v23, v24, v21
	v_fma_f32 v20, -v20, v23, v22
	v_div_fmas_f32 v20, v20, v21, v23
	v_div_fixup_f32 v19, v20, v19, v5
	v_div_scale_f32 v5, s[10:11], v18, v18, v15
	v_rcp_f32_e32 v20, v5
	s_nop 0
	v_fma_f32 v21, -v5, v20, 1.0
	v_fmac_f32_e32 v20, v21, v20
	v_div_scale_f32 v21, vcc, v15, v18, v15
	v_mul_f32_e32 v22, v21, v20
	v_fma_f32 v23, -v5, v22, v21
	v_fmac_f32_e32 v22, v23, v20
	v_fma_f32 v5, -v5, v22, v21
	v_div_fmas_f32 v5, v5, v20, v22
	v_div_fixup_f32 v18, v5, v18, v15
	v_pk_mul_f32 v[16:17], v[18:19], v[16:17]
	s_nop 0
	v_cvt_pk_bf16_f32 v5, v16, v17
	v_add_co_u32_e32 v16, vcc, s5, v12
	s_mov_b32 s5, 0x21fb000
	s_nop 0
	v_addc_co_u32_e32 v17, vcc, 0, v13, vcc
	v_add_co_u32_e32 v10, vcc, s5, v10
	global_store_dwordx4 v[16:17], v[2:5], off offset:1536
	s_nop 0
	v_addc_co_u32_e32 v11, vcc, 0, v11, vcc
	ds_read_b128 v[2:5], v14 offset:26112
	global_load_dwordx4 v[14:17], v[10:11], off offset:1536
	s_waitcnt lgkmcnt(0)
	v_lshlrev_b32_e32 v10, 16, v2
	v_and_b32_e32 v11, 0xffff0000, v2
	s_waitcnt vmcnt(0)
	v_lshlrev_b32_e32 v20, 16, v14
	v_and_b32_e32 v2, 0xffff0000, v14
	v_mul_f32_e32 v14, 0xbfb8aa3b, v20
	v_exp_f32_e32 v18, v14
	v_mul_f32_e32 v14, 0xbfb8aa3b, v2
	v_exp_f32_e32 v19, v14
	s_nop 0
	v_pk_add_f32 v[18:19], v[18:19], 1.0 op_sel_hi:[1,0]
	s_nop 0
	v_div_scale_f32 v14, s[10:11], v19, v19, v2
	v_rcp_f32_e32 v21, v14
	s_nop 0
	v_fma_f32 v22, -v14, v21, 1.0
	v_fmac_f32_e32 v21, v22, v21
	v_div_scale_f32 v22, vcc, v2, v19, v2
	v_mul_f32_e32 v23, v22, v21
	v_fma_f32 v24, -v14, v23, v22
	v_fmac_f32_e32 v23, v24, v21
	v_fma_f32 v14, -v14, v23, v22
	v_div_fmas_f32 v14, v14, v21, v23
	v_div_fixup_f32 v19, v14, v19, v2
	v_div_scale_f32 v2, s[10:11], v18, v18, v20
	v_rcp_f32_e32 v14, v2
	s_nop 0
	v_fma_f32 v21, -v2, v14, 1.0
	v_fmac_f32_e32 v14, v21, v14
	v_div_scale_f32 v21, vcc, v20, v18, v20
	v_mul_f32_e32 v22, v21, v14
	v_fma_f32 v23, -v2, v22, v21
	v_fmac_f32_e32 v22, v23, v14
	v_fma_f32 v2, -v2, v22, v21
	v_div_fmas_f32 v2, v2, v14, v22
	v_div_fixup_f32 v18, v2, v18, v20
	v_pk_mul_f32 v[10:11], v[18:19], v[10:11]
	v_lshlrev_b32_e32 v18, 16, v15
	v_cvt_pk_bf16_f32 v2, v10, v11
	v_lshlrev_b32_e32 v10, 16, v3
	v_and_b32_e32 v11, 0xffff0000, v3
	v_and_b32_e32 v3, 0xffff0000, v15
	v_mul_f32_e32 v14, 0xbfb8aa3b, v18
	v_mul_f32_e32 v15, 0xbfb8aa3b, v3
	v_exp_f32_e32 v14, v14
	v_exp_f32_e32 v15, v15
	s_nop 0
	v_pk_add_f32 v[14:15], v[14:15], 1.0 op_sel_hi:[1,0]
	s_nop 0
	v_div_scale_f32 v19, s[10:11], v15, v15, v3
	v_rcp_f32_e32 v20, v19
	s_nop 0
	v_fma_f32 v21, -v19, v20, 1.0
	v_fmac_f32_e32 v20, v21, v20
	v_div_scale_f32 v21, vcc, v3, v15, v3
	v_mul_f32_e32 v22, v21, v20
	v_fma_f32 v23, -v19, v22, v21
	v_fmac_f32_e32 v22, v23, v20
	v_fma_f32 v19, -v19, v22, v21
	v_div_fmas_f32 v19, v19, v20, v22
	v_div_fixup_f32 v15, v19, v15, v3
	v_div_scale_f32 v3, s[10:11], v14, v14, v18
	v_rcp_f32_e32 v19, v3
	s_nop 0
	v_fma_f32 v20, -v3, v19, 1.0
	v_fmac_f32_e32 v19, v20, v19
	v_div_scale_f32 v20, vcc, v18, v14, v18
	v_mul_f32_e32 v21, v20, v19
	v_fma_f32 v22, -v3, v21, v20
	v_fmac_f32_e32 v21, v22, v19
	v_fma_f32 v3, -v3, v21, v20
	v_div_fmas_f32 v3, v3, v19, v21
	v_div_fixup_f32 v14, v3, v14, v18
	v_pk_mul_f32 v[10:11], v[14:15], v[10:11]
	v_lshlrev_b32_e32 v18, 16, v16
	v_cvt_pk_bf16_f32 v3, v10, v11
	v_lshlrev_b32_e32 v10, 16, v4
	v_and_b32_e32 v11, 0xffff0000, v4
	v_and_b32_e32 v4, 0xffff0000, v16
	v_mul_f32_e32 v14, 0xbfb8aa3b, v18
	v_mul_f32_e32 v15, 0xbfb8aa3b, v4
	v_exp_f32_e32 v14, v14
	v_exp_f32_e32 v15, v15
	s_nop 0
	v_pk_add_f32 v[14:15], v[14:15], 1.0 op_sel_hi:[1,0]
	s_nop 0
	v_div_scale_f32 v16, s[10:11], v15, v15, v4
	v_rcp_f32_e32 v19, v16
	s_nop 0
	v_fma_f32 v20, -v16, v19, 1.0
	v_fmac_f32_e32 v19, v20, v19
	v_div_scale_f32 v20, vcc, v4, v15, v4
	v_mul_f32_e32 v21, v20, v19
	v_fma_f32 v22, -v16, v21, v20
	v_fmac_f32_e32 v21, v22, v19
	v_fma_f32 v16, -v16, v21, v20
	v_div_fmas_f32 v16, v16, v19, v21
	v_div_fixup_f32 v15, v16, v15, v4
	v_div_scale_f32 v4, s[10:11], v14, v14, v18
	v_rcp_f32_e32 v16, v4
	s_nop 0
	v_fma_f32 v19, -v4, v16, 1.0
	v_fmac_f32_e32 v16, v19, v16
	v_div_scale_f32 v19, vcc, v18, v14, v18
	v_mul_f32_e32 v20, v19, v16
	v_fma_f32 v21, -v4, v20, v19
	v_fmac_f32_e32 v20, v21, v16
	v_fma_f32 v4, -v4, v20, v19
	v_div_fmas_f32 v4, v4, v16, v20
	v_div_fixup_f32 v14, v4, v14, v18
	v_pk_mul_f32 v[10:11], v[14:15], v[10:11]
	v_lshlrev_b32_e32 v16, 16, v17
	v_cvt_pk_bf16_f32 v4, v10, v11
	v_lshlrev_b32_e32 v10, 16, v5
	v_and_b32_e32 v11, 0xffff0000, v5
	v_and_b32_e32 v5, 0xffff0000, v17
	v_mul_f32_e32 v14, 0xbfb8aa3b, v16
	v_mul_f32_e32 v15, 0xbfb8aa3b, v5
	v_exp_f32_e32 v14, v14
	v_exp_f32_e32 v15, v15
	s_nop 0
	v_pk_add_f32 v[14:15], v[14:15], 1.0 op_sel_hi:[1,0]
	s_nop 0
	v_div_scale_f32 v17, s[10:11], v15, v15, v5
	v_rcp_f32_e32 v18, v17
	s_nop 0
	v_fma_f32 v19, -v17, v18, 1.0
	v_fmac_f32_e32 v18, v19, v18
	v_div_scale_f32 v19, vcc, v5, v15, v5
	v_mul_f32_e32 v20, v19, v18
	v_fma_f32 v21, -v17, v20, v19
	v_fmac_f32_e32 v20, v21, v18
	v_fma_f32 v17, -v17, v20, v19
	v_div_fmas_f32 v17, v17, v18, v20
	v_div_fixup_f32 v15, v17, v15, v5
	v_div_scale_f32 v5, s[10:11], v14, v14, v16
	v_rcp_f32_e32 v17, v5
	s_nop 0
	v_fma_f32 v18, -v5, v17, 1.0
	v_fmac_f32_e32 v17, v18, v17
	v_div_scale_f32 v18, vcc, v16, v14, v16
	v_mul_f32_e32 v19, v18, v17
	v_fma_f32 v20, -v5, v19, v18
	v_fmac_f32_e32 v19, v20, v17
	v_fma_f32 v5, -v5, v19, v18
	v_div_fmas_f32 v5, v5, v17, v19
	v_div_fixup_f32 v14, v5, v14, v16
	v_pk_mul_f32 v[10:11], v[14:15], v[10:11]
	s_nop 0
	v_cvt_pk_bf16_f32 v5, v10, v11
	v_add_co_u32_e32 v10, vcc, 0x373cb000, v12
	s_nop 1
	v_addc_co_u32_e32 v11, vcc, 0, v13, vcc
	global_store_dwordx4 v[10:11], v[2:5], off offset:1536
	s_cbranch_scc0 .LBB0_41
	v_readlane_b32 s4, v254, 3
	s_add_i32 s6, s6, s4
	s_cmpk_gt_i32 s6, 0x4ff
	s_barrier
	s_cbranch_scc0 .LBB0_21
	v_readlane_b32 s0, v255, 62
	s_nop 3
	s_cmp_eq_u32 s0, 2
	s_cbranch_scc0 .LBB0_43
	s_mov_b32 s0, 0
	s_nop 0
	v_writelane_b32 v255, s0, 62
	s_branch .LBB0_94

.Lp4_ret_done:
	v_readlane_b32 s0, v255, 62
	s_nop 3
	s_cmp_eq_u32 s0, 1
	s_cbranch_scc0 .LBB0_94
	s_mov_b32 s0, 2
	s_nop 0
	v_writelane_b32 v255, s0, 62
	s_branch .Lp4_attn_entry
